# late-needed weight transposes moved out of P0 into idle-workgroup holes: Wt_out+Wt_fi in P2's last round, Wt_fo in P7's last round
# baseline (speedup 1.0000x reference)
; __global__ void __launch_bounds__(512, 2) mega_fwd(Args a) {
;     ...
;         constexpr int I_IN = 16 * 56, I_UQ = 6 * 24, I_UKV = 4 * 32, I_OUT = 16 * 32, I_FI = 16 * 176, I_FO = 44 * 32, I_CKV = 4096, I_CKR = 2048, I_ROPE = 1024, I_WM = 1024;
;         constexpr int NITEMS = I_IN + I_UQ + I_UKV + I_OUT + I_FI + I_FO + I_CKV + I_CKR + I_ROPE + I_WM;
;         for (int it = gw; it < NITEMS; it += NGW) {
;             int r = it;
;             if (r < I_IN) { const int kb = r / 56, nb = r % 56, n0 = nb * 32;
;                 const int c0 = n0 < 512 ? n0 : n0 < 768 ? 1408 + (n0 - 512) : n0 < 1152 ? 1024 + (n0 - 768) : n0 < 1184 ? 1664 : n0 < 1280 ? -1 : 512 + (n0 - 1280);
;                 p0_transpose_item(w_in, 1696, c0, kb * 64, Wt_in, 1024, n0, nullptr, scr, lane); continue; } r -= I_IN;
;             if (r < I_UQ) { const int kb = r / 24, nb = r % 24, pn = nb >> 3, bj = (nb >> 2) & 1, wc = nb & 3;
;                 const int c0 = pn < 2 ? 96 * (4 * pn + wc) + 32 * bj : 96 * (4 * bj + wc) + 64;
;                 p0_transpose_item(w_uq, 768, c0, kb * 64, Wt_uq, 384, nb * 32, q_norm_g, scr, lane); continue; } r -= I_UQ;
;             if (r < I_UKV) { const int kb = r / 32, nb = r % 32; int c0;
;                 if (nb < 16) { const int pn = nb >> 3, bj = (nb >> 2) & 1, wc = nb & 3; c0 = 128 * (4 * pn + wc) + 32 * bj; }
;                 else { const int ch0 = (nb - 16) * 32; c0 = 128 * (ch0 >> 6) + 64 + (ch0 & 63); }
;                 p0_transpose_item(w_ukv, 1024, c0, kb * 64, Wt_ukv, 256, nb * 32, nullptr, scr, lane); continue; } r -= I_UKV;
;             if (r < I_OUT) { const int kb = r / 32, nb = r % 32; p0_transpose_item(w_out, 1024, nb * 32, kb * 64, Wt_out, 1024, nb * 32, nullptr, scr, lane); continue; } r -= I_OUT;
;             if (r < I_FI) { const int kb = r / 176, nb = r % 176, n0 = nb * 32, pn = n0 >> 8, bj = (n0 >> 7) & 1, rr = n0 & 127;
;                 p0_transpose_item(w_fi, 5632, bj * 2816 + 128 * pn + rr, kb * 64, Wt_fi, 1024, n0, nullptr, scr, lane); continue; } r -= I_FI;
;             if (r < I_FO) { const int kb = r / 32, nb = r % 32; p0_transpose_item(w_fo, 1024, nb * 32, kb * 64, Wt_fo, 2816, nb * 32, nullptr, scr, lane); continue; } r -= I_FO;
.LBB0_22:
	s_cmpk_lt_u32 s3, 0x490
	s_cbranch_scc1 .Lp0_keep
	s_cmpk_lt_u32 s3, 0x1710
	s_cbranch_scc1 .LBB0_21

; #define LAS __attribute__((address_space(3)))
; __device__ __forceinline__ unsigned cvt_pk_bf16(float lo, float hi) { unsigned r; asm("v_cvt_pk_bf16_f32 %0, %1, %2" : "=v"(r) : "v"(lo), "v"(hi)); return r; }
; #define LDS_WAIT() asm volatile("s_waitcnt lgkmcnt(0)" ::: "memory")
; __device__ __forceinline__ void p0_transpose_item(const float* W, int ldw, int c0, int k0, bf16_t* WT, int K, int n0, const float* kscale, LAS float* scr, int lane) {
; #pragma unroll
;     for (int i = 0; i < 32; ++i) { const int kk = 2 * i + (lane >> 5); float v = 0.f;
;         if (c0 >= 0) v = __builtin_nontemporal_load(W + (size_t)(k0 + kk) * ldw + c0 + (lane & 31));
;         if (kscale) v *= kscale[k0 + kk];
;         scr[kk * 33 + (lane & 31)] = v; }
;     LDS_WAIT(); asm volatile("" ::: "memory");
;     const int c = lane & 7;
; #pragma unroll
;     for (int j = 0; j < 4; ++j) { const int n = (lane >> 3) + 8 * j; const LAS float* s = scr + (8 * c) * 33 + n;
;         u32x4 o; o.x = cvt_pk_bf16(s[0 * 33], s[1 * 33]); o.y = cvt_pk_bf16(s[2 * 33], s[3 * 33]); o.z = cvt_pk_bf16(s[4 * 33], s[5 * 33]); o.w = cvt_pk_bf16(s[6 * 33], s[7 * 33]);
;         *(u32x4*)(WT + (size_t)(n0 + n) * K + k0 + 8 * c) = o; }
; __global__ void __launch_bounds__(512, 2) mega_fwd(Args a) {
;     ...
;             if (r < I_OUT) { const int kb = r / 32, nb = r % 32; p0_transpose_item(w_out, 1024, nb * 32, kb * 64, Wt_out, 1024, nb * 32, nullptr, scr, lane); continue; } r -= I_OUT;
;             if (r < I_FI) { const int kb = r / 176, nb = r % 176, n0 = nb * 32, pn = n0 >> 8, bj = (n0 >> 7) & 1, rr = n0 & 127;
;                 p0_transpose_item(w_fi, 5632, bj * 2816 + 128 * pn + rr, kb * 64, Wt_fi, 1024, n0, nullptr, scr, lane); continue; } r -= I_FI;
.LBB0_488:
	s_cmpk_lt_i32 s2, 0x8e
	s_cbranch_scc1 .Lht1_skip
	v_writelane_b32 v239, s0, 8
	v_writelane_b32 v239, s1, 9
	v_writelane_b32 v239, s3, 10
	v_writelane_b32 v239, s4, 11
	v_writelane_b32 v239, s5, 12
	v_writelane_b32 v239, s6, 13
	v_writelane_b32 v239, s7, 14
	v_writelane_b32 v239, s8, 15
	v_writelane_b32 v239, s9, 16
	v_writelane_b32 v239, s10, 17
	v_writelane_b32 v239, s11, 18
	v_writelane_b32 v239, s21, 19
	v_writelane_b32 v239, s22, 20
	v_writelane_b32 v239, s23, 21
	v_writelane_b32 v239, s24, 22
	v_writelane_b32 v239, s25, 23
	v_writelane_b32 v239, s40, 24
	v_writelane_b32 v239, s41, 25
	v_writelane_b32 v239, s42, 26
	v_writelane_b32 v239, s43, 27
	v_writelane_b32 v239, vcc_lo, 30
	v_writelane_b32 v239, vcc_hi, 31
	v_readfirstlane_b32 s21, v211
	s_ashr_i32 s21, s21, 6
	s_sub_i32 s3, s2, 0x8e
	s_lshl_b32 s3, s3, 3
	s_add_i32 s3, s3, s21
	s_cmpk_lt_u32 s3, 0xd00
	s_cbranch_scc0 .Lht1_exit
	s_lshl_b32 s21, s21, 14
	v_and_b32_e32 v0, 63, v211
	v_lshrrev_b32_e32 v1, 5, v0
	v_and_b32_e32 v2, 31, v0
	v_and_b32_e32 v3, 7, v0
	v_lshrrev_b32_e32 v4, 3, v0
	v_mul_u32_u24_e32 v5, 33, v1
	v_add_lshl_u32 v5, v5, v2, 2
	v_add_u32_e32 v5, s21, v5
	v_mul_u32_u24_e32 v8, 0x108, v3
	v_add_lshl_u32 v8, v8, v4, 2
	v_add_u32_e32 v8, s21, v8
	s_cmpk_lt_u32 s3, 0x200
	s_cbranch_scc0 .Lht11_not_out
	s_lshr_b32 s22, s3, 5
	s_and_b32 s23, s3, 31
	s_lshl_b32 s23, s23, 5
	s_mov_b32 s8, s23
	v_readlane_b32 s4, v239, 0
	v_readlane_b32 s5, v239, 1
	s_movk_i32 s25, 0x400
	s_movk_i32 s9, 0x400
	s_mov_b32 s0, 0xa00000
	s_branch .Lht11_go

; #define LAS __attribute__((address_space(3)))
; __device__ __forceinline__ unsigned cvt_pk_bf16(float lo, float hi) { unsigned r; asm("v_cvt_pk_bf16_f32 %0, %1, %2" : "=v"(r) : "v"(lo), "v"(hi)); return r; }
; #define LDS_WAIT() asm volatile("s_waitcnt lgkmcnt(0)" ::: "memory")
; __device__ __forceinline__ void p0_transpose_item(const float* W, int ldw, int c0, int k0, bf16_t* WT, int K, int n0, const float* kscale, LAS float* scr, int lane) {
; #pragma unroll
;     for (int i = 0; i < 32; ++i) { const int kk = 2 * i + (lane >> 5); float v = 0.f;
;         if (c0 >= 0) v = __builtin_nontemporal_load(W + (size_t)(k0 + kk) * ldw + c0 + (lane & 31));
;         if (kscale) v *= kscale[k0 + kk];
;         scr[kk * 33 + (lane & 31)] = v; }
;     LDS_WAIT(); asm volatile("" ::: "memory");
;     const int c = lane & 7;
; #pragma unroll
;     for (int j = 0; j < 4; ++j) { const int n = (lane >> 3) + 8 * j; const LAS float* s = scr + (8 * c) * 33 + n;
;         u32x4 o; o.x = cvt_pk_bf16(s[0 * 33], s[1 * 33]); o.y = cvt_pk_bf16(s[2 * 33], s[3 * 33]); o.z = cvt_pk_bf16(s[4 * 33], s[5 * 33]); o.w = cvt_pk_bf16(s[6 * 33], s[7 * 33]);
;         *(u32x4*)(WT + (size_t)(n0 + n) * K + k0 + 8 * c) = o; }
; __global__ void __launch_bounds__(512, 2) mega_fwd(Args a) {
;     ...
;             if (r < I_FO) { const int kb = r / 32, nb = r % 32; p0_transpose_item(w_fo, 1024, nb * 32, kb * 64, Wt_fo, 2816, nb * 32, nullptr, scr, lane); continue; } r -= I_FO;
.LBB0_1184:
	s_cmpk_lt_i32 s2, 0x2c
	s_cbranch_scc1 .Lht2_skip
	v_writelane_b32 v239, s0, 8
	v_writelane_b32 v239, s1, 9
	v_writelane_b32 v239, s3, 10
	v_writelane_b32 v239, s4, 11
	v_writelane_b32 v239, s5, 12
	v_writelane_b32 v239, s6, 13
	v_writelane_b32 v239, s7, 14
	v_writelane_b32 v239, s8, 15
	v_writelane_b32 v239, s9, 16
	v_writelane_b32 v239, s10, 17
	v_writelane_b32 v239, s11, 18
	v_writelane_b32 v239, s21, 19
	v_writelane_b32 v239, s22, 20
	v_writelane_b32 v239, s23, 21
	v_writelane_b32 v239, s24, 22
	v_writelane_b32 v239, s25, 23
	v_writelane_b32 v239, s40, 24
	v_writelane_b32 v239, s41, 25
	v_writelane_b32 v239, s42, 26
	v_writelane_b32 v239, s43, 27
	v_writelane_b32 v239, vcc_lo, 30
	v_writelane_b32 v239, vcc_hi, 31
	v_readfirstlane_b32 s21, v211
	s_ashr_i32 s21, s21, 6
	s_sub_i32 s3, s2, 0x2c
	s_lshl_b32 s3, s3, 3
	s_add_i32 s3, s3, s21
	s_addk_i32 s3, 0xd00
	s_cmpk_lt_u32 s3, 0x1280
	s_cbranch_scc0 .Lht2_exit
	s_lshl_b32 s21, s21, 14
	v_and_b32_e32 v0, 63, v211
	v_lshrrev_b32_e32 v1, 5, v0
	v_and_b32_e32 v2, 31, v0
	v_and_b32_e32 v3, 7, v0
	v_lshrrev_b32_e32 v4, 3, v0
	v_mul_u32_u24_e32 v5, 33, v1
	v_add_lshl_u32 v5, v5, v2, 2
	v_add_u32_e32 v5, s21, v5
	v_mul_u32_u24_e32 v8, 0x108, v3
	v_add_lshl_u32 v8, v8, v4, 2
	v_add_u32_e32 v8, s21, v8
	s_cmpk_lt_u32 s3, 0x200
	s_cbranch_scc0 .Lht21_not_out
	s_lshr_b32 s22, s3, 5
	s_and_b32 s23, s3, 31
	s_lshl_b32 s23, s23, 5
	s_mov_b32 s8, s23
	v_readlane_b32 s4, v239, 0
	v_readlane_b32 s5, v239, 1
	s_movk_i32 s25, 0x400
	s_movk_i32 s9, 0x400
	s_mov_b32 s0, 0xa00000
	s_branch .Lht21_go

; __global__ void __launch_bounds__(512, 2) mega_fwd(Args a) {
;     ...
;         for (int it = gw; it < NITEMS; it += NGW) {
;     ...
;             if (r < I_OUT) { const int kb = r / 32, nb = r % 32; p0_transpose_item(w_out, 1024, nb * 32, kb * 64, Wt_out, 1024, nb * 32, nullptr, scr, lane); continue; } r -= I_OUT;
;             if (r < I_FI) { const int kb = r / 176, nb = r % 176, n0 = nb * 32, pn = n0 >> 8, bj = (n0 >> 7) & 1, rr = n0 & 127;
;                 p0_transpose_item(w_fi, 5632, bj * 2816 + 128 * pn + rr, kb * 64, Wt_fi, 1024, n0, nullptr, scr, lane); continue; } r -= I_FI;
;             if (r < I_FO) { const int kb = r / 32, nb = r % 32; p0_transpose_item(w_fo, 1024, nb * 32, kb * 64, Wt_fo, 2816, nb * 32, nullptr, scr, lane); continue; } r -= I_FO;
.Lht2_loop:
	s_addk_i32 s3, 0x6a0
	s_cmpk_lt_u32 s3, 0x1280
	s_cselect_b32 s43, 1, 0
	s_cbranch_scc0 .Lht2_a_last
	s_cmpk_lt_u32 s3, 0x200
	s_cbranch_scc0 .Lht22_not_out
	s_lshr_b32 s22, s3, 5
	s_and_b32 s23, s3, 31
	s_lshl_b32 s23, s23, 5
	s_mov_b32 s8, s23
	v_readlane_b32 s4, v239, 0
	v_readlane_b32 s5, v239, 1
	s_movk_i32 s25, 0x400
	s_movk_i32 s9, 0x400
	s_mov_b32 s0, 0xa00000
	s_branch .Lht22_go

; #define LAS __attribute__((address_space(3)))
; __device__ __forceinline__ unsigned cvt_pk_bf16(float lo, float hi) { unsigned r; asm("v_cvt_pk_bf16_f32 %0, %1, %2" : "=v"(r) : "v"(lo), "v"(hi)); return r; }
; #define LDS_WAIT() asm volatile("s_waitcnt lgkmcnt(0)" ::: "memory")
; __device__ __forceinline__ void p0_transpose_item(const float* W, int ldw, int c0, int k0, bf16_t* WT, int K, int n0, const float* kscale, LAS float* scr, int lane) {
;     ...
;     LDS_WAIT(); asm volatile("" ::: "memory");
;     const int c = lane & 7;
; #pragma unroll
;     for (int j = 0; j < 4; ++j) { const int n = (lane >> 3) + 8 * j; const LAS float* s = scr + (8 * c) * 33 + n;
;         u32x4 o; o.x = cvt_pk_bf16(s[0 * 33], s[1 * 33]); o.y = cvt_pk_bf16(s[2 * 33], s[3 * 33]); o.z = cvt_pk_bf16(s[4 * 33], s[5 * 33]); o.w = cvt_pk_bf16(s[6 * 33], s[7 * 33]);
;         *(u32x4*)(WT + (size_t)(n0 + n) * K + k0 + 8 * c) = o; }
;     LDS_WAIT(); asm volatile("" ::: "memory");
; }
.Lht2_a_proc:
	ds_write_b32 v5, v10
	ds_write_b32 v5, v11 offset:264
	ds_write_b32 v5, v12 offset:528
	ds_write_b32 v5, v13 offset:792
	ds_write_b32 v5, v14 offset:1056
	ds_write_b32 v5, v15 offset:1320
	ds_write_b32 v5, v16 offset:1584
	ds_write_b32 v5, v17 offset:1848
	ds_write_b32 v5, v18 offset:2112
	ds_write_b32 v5, v19 offset:2376
	ds_write_b32 v5, v20 offset:2640
	ds_write_b32 v5, v21 offset:2904
	ds_write_b32 v5, v22 offset:3168
	ds_write_b32 v5, v23 offset:3432
	ds_write_b32 v5, v24 offset:3696
	ds_write_b32 v5, v25 offset:3960
	ds_write_b32 v5, v26 offset:4224
	ds_write_b32 v5, v27 offset:4488
	ds_write_b32 v5, v28 offset:4752
	ds_write_b32 v5, v29 offset:5016
	ds_write_b32 v5, v30 offset:5280
	ds_write_b32 v5, v31 offset:5544
	ds_write_b32 v5, v32 offset:5808
	ds_write_b32 v5, v33 offset:6072
	ds_write_b32 v5, v34 offset:6336
	ds_write_b32 v5, v35 offset:6600
	ds_write_b32 v5, v36 offset:6864
	ds_write_b32 v5, v37 offset:7128
	ds_write_b32 v5, v38 offset:7392
	ds_write_b32 v5, v39 offset:7656
	ds_write_b32 v5, v40 offset:7920
	ds_write_b32 v5, v41 offset:8184
	s_waitcnt lgkmcnt(0)
	ds_read_b32 v50, v8
	ds_read_b32 v51, v8 offset:132
	ds_read_b32 v52, v8 offset:264
	ds_read_b32 v53, v8 offset:396
	ds_read_b32 v54, v8 offset:528
	ds_read_b32 v55, v8 offset:660
	ds_read_b32 v56, v8 offset:792
	ds_read_b32 v57, v8 offset:924
	s_waitcnt lgkmcnt(0)
	v_cvt_pk_bf16_f32 v58, v50, v51
	v_cvt_pk_bf16_f32 v59, v52, v53
	v_cvt_pk_bf16_f32 v60, v54, v55
	v_cvt_pk_bf16_f32 v61, v56, v57
	global_store_dwordx4 v62, v[58:61], s[10:11]
	s_add_u32 s10, s10, s24
	s_addc_u32 s11, s11, 0
	s_nop 1
	ds_read_b32 v50, v8 offset:32
	ds_read_b32 v51, v8 offset:164
	ds_read_b32 v52, v8 offset:296
	ds_read_b32 v53, v8 offset:428
	ds_read_b32 v54, v8 offset:560
	ds_read_b32 v55, v8 offset:692
	ds_read_b32 v56, v8 offset:824
	ds_read_b32 v57, v8 offset:956
	s_waitcnt lgkmcnt(0)
	v_cvt_pk_bf16_f32 v58, v50, v51
	v_cvt_pk_bf16_f32 v59, v52, v53
	v_cvt_pk_bf16_f32 v60, v54, v55
	v_cvt_pk_bf16_f32 v61, v56, v57
	global_store_dwordx4 v62, v[58:61], s[10:11]
	s_add_u32 s10, s10, s24
	s_addc_u32 s11, s11, 0
	s_nop 1
	ds_read_b32 v50, v8 offset:64
	ds_read_b32 v51, v8 offset:196
	ds_read_b32 v52, v8 offset:328
	ds_read_b32 v53, v8 offset:460
	ds_read_b32 v54, v8 offset:592
	ds_read_b32 v55, v8 offset:724
	ds_read_b32 v56, v8 offset:856
	ds_read_b32 v57, v8 offset:988
	s_waitcnt lgkmcnt(0)
	v_cvt_pk_bf16_f32 v58, v50, v51
	v_cvt_pk_bf16_f32 v59, v52, v53
	v_cvt_pk_bf16_f32 v60, v54, v55
	v_cvt_pk_bf16_f32 v61, v56, v57
	global_store_dwordx4 v62, v[58:61], s[10:11]
	s_add_u32 s10, s10, s24
	s_addc_u32 s11, s11, 0
	s_nop 1
	ds_read_b32 v50, v8 offset:96
	ds_read_b32 v51, v8 offset:228
	ds_read_b32 v52, v8 offset:360
	ds_read_b32 v53, v8 offset:492
	ds_read_b32 v54, v8 offset:624
	ds_read_b32 v55, v8 offset:756
	ds_read_b32 v56, v8 offset:888
	ds_read_b32 v57, v8 offset:1020
	s_waitcnt lgkmcnt(0)
	v_cvt_pk_bf16_f32 v58, v50, v51
	v_cvt_pk_bf16_f32 v59, v52, v53
	v_cvt_pk_bf16_f32 v60, v54, v55
	v_cvt_pk_bf16_f32 v61, v56, v57
	global_store_dwordx4 v62, v[58:61], s[10:11]
	s_nop 1
	s_cmp_eq_u32 s43, 0
	s_cbranch_scc1 .Lht2_exit
	s_addk_i32 s3, 0x6a0
	s_cmpk_lt_u32 s3, 0x1280
	s_cselect_b32 s43, 1, 0
	s_cbranch_scc0 .Lht2_b_last
	s_cmpk_lt_u32 s3, 0x200
	s_cbranch_scc0 .Lht23_not_out
	s_lshr_b32 s22, s3, 5
	s_and_b32 s23, s3, 31
	s_lshl_b32 s23, s23, 5
	s_mov_b32 s8, s23
	v_readlane_b32 s4, v239, 0
	v_readlane_b32 s5, v239, 1
	s_movk_i32 s25, 0x400
	s_movk_i32 s9, 0x400
	s_mov_b32 s0, 0xa00000
	s_branch .Lht23_go

; __device__ __forceinline__ unsigned xb_ld(unsigned* p)              { return __hip_atomic_load(p, __ATOMIC_RELAXED, __HIP_MEMORY_SCOPE_AGENT); }
; __device__ __forceinline__ void xcd_barrier_complete(unsigned* bar, unsigned x, unsigned& nloc, unsigned& nx) {
;     const unsigned G = gridDim.x * gridDim.y * gridDim.z;
;     unsigned sum, cnt, mine, sp = 0u;
;     for (;;) {
;         sum = 0u; cnt = 0u; mine = 0u;
; #pragma unroll
;         for (unsigned j = 0; j < 16; ++j) { const unsigned c = xb_ld(&bar[XB_XCNT(j)]); sum += c; cnt += (c > 0u) ? 1u : 0u; mine = (j == x) ? c : mine; }
;         if (sum == G) break;
;         __builtin_amdgcn_s_sleep(1);
;         if ((++sp & 255u) == 0u) { if (xb_ld(&bar[XB_TMO])) break; if (sp > XB_SPIN_CAP) { atomicAdd(&bar[XB_TMO], 1u); break; } }
;     }
;     nloc = mine > 0u ? mine : 1u; nx = cnt > 0u ? cnt : 1u;
; }
; __device__ __forceinline__ void xcd_barrier(const XcdBarrier& b) {
;     asm volatile("s_waitcnt vmcnt(0)" ::: "memory");
;     __syncthreads();
;     if (threadIdx.x == 0) {
;         unsigned* bar = b.bar;
;         __builtin_amdgcn_s_waitcnt(0);
;         unsigned nloc = b.st[0], nx = b.st[1];
;         if (nloc == 0u) { xcd_barrier_complete(bar, b.x, nloc, nx); b.st[0] = nloc; b.st[1] = nx; }
.Lht2_exit:
	v_readlane_b32 s0, v239, 8
	v_readlane_b32 s1, v239, 9
	v_readlane_b32 s3, v239, 10
	v_readlane_b32 s4, v239, 11
	v_readlane_b32 s5, v239, 12
	v_readlane_b32 s6, v239, 13
	v_readlane_b32 s7, v239, 14
	v_readlane_b32 s8, v239, 15
	v_readlane_b32 s9, v239, 16
	v_readlane_b32 s10, v239, 17
	v_readlane_b32 s11, v239, 18
	v_readlane_b32 s21, v239, 19
	v_readlane_b32 s22, v239, 20
	v_readlane_b32 s23, v239, 21
	v_readlane_b32 s24, v239, 22
	v_readlane_b32 s25, v239, 23
	v_readlane_b32 s40, v239, 24
	v_readlane_b32 s41, v239, 25
	v_readlane_b32 s42, v239, 26
	v_readlane_b32 s43, v239, 27
	v_readlane_b32 vcc_lo, v239, 30
	v_readlane_b32 vcc_hi, v239, 31
.Lht2_skip:
	s_waitcnt vmcnt(0)
	s_waitcnt vmcnt(0)
	s_barrier
	s_mov_b64 s[0:1], exec
	v_readlane_b32 s8, v238, 2
	v_readlane_b32 s9, v238, 3
	s_and_b64 s[8:9], s[0:1], s[8:9]
	s_mov_b64 exec, s[8:9]
	s_cbranch_execz .LBB0_1236
	s_add_i32 s7, 0, 0x22000
	v_mov_b32_e32 v0, s7
	s_waitcnt vmcnt(0) expcnt(0) lgkmcnt(0)
	ds_read_b32 v2, v0
	s_add_i32 s7, 0, 0x22004
	v_mov_b32_e32 v0, s7
	ds_read_b32 v0, v0
	s_waitcnt lgkmcnt(1)
	v_cmp_ne_u32_e32 vcc, 0, v2
	s_cbranch_vccnz .LBB0_1200
	s_add_u32 s8, s30, 0x2f8200
	s_addc_u32 s9, s31, 0
	s_add_u32 s10, s30, 0x2f8400
	s_addc_u32 s11, s31, 0
	s_add_u32 s12, s30, 0x2f8500
	s_addc_u32 s13, s31, 0
	s_add_u32 s14, s30, 0x2f8600
	s_addc_u32 s15, s31, 0
	s_add_u32 s18, s30, 0x2f8700
	s_addc_u32 s19, s31, 0
	s_add_u32 s24, s30, 0x2f8800
	s_addc_u32 s25, s31, 0
	s_add_u32 s26, s30, 0x2f8900
	s_addc_u32 s27, s31, 0
	s_add_u32 s36, s30, 0x2f8a00
	s_addc_u32 s37, s31, 0
	s_add_u32 s38, s30, 0x2f8b00
	s_addc_u32 s39, s31, 0
	s_add_u32 s40, s30, 0x2f8c00
	s_addc_u32 s41, s31, 0
	s_add_u32 s42, s30, 0x2f8d00
	s_addc_u32 s43, s31, 0
	s_add_u32 s44, s30, 0x2f8e00
	s_addc_u32 s45, s31, 0
	s_add_u32 s46, s30, 0x2f8f00
	s_addc_u32 s47, s31, 0
	s_add_u32 s48, s30, 0x2f9000
	s_addc_u32 s49, s31, 0
	s_add_u32 s50, s30, 0x2f9100
	s_addc_u32 s51, s31, 0
	s_add_u32 s52, s30, 0x2f9200
	v_readlane_b32 s7, v238, 0
	s_addc_u32 s53, s31, 0
	s_mul_i32 s7, s35, s7
	s_add_u32 s54, s30, 0x2f9300
	s_mul_i32 s7, s7, s34
	s_addc_u32 s55, s31, 0
	s_mov_b32 s21, 1
	v_mov_b32_e32 v16, 0
	s_branch .LBB0_1188
